# P9 epilogue first half: counted waits (vmcnt 15 per load group) so residual add/stores start as loads return, instead of waiting for all sixteen
# baseline (speedup 1.0000x reference)
.LBB0_1615:
	v_lshlrev_b64 v[198:199], 2, v[196:197]
	v_lshl_add_u64 v[178:179], s[14:15], 0, v[198:199]
	v_lshlrev_b64 v[184:185], 12, v[190:191]
	v_lshl_add_u64 v[142:143], v[178:179], 0, v[184:185]
	global_load_dwordx4 v[130:133], v[142:143], off
	global_load_dwordx4 v[134:137], v[142:143], off offset:64
	global_load_dwordx4 v[138:141], v[142:143], off offset:512
	s_nop 0
	global_load_dwordx4 v[142:145], v[142:143], off offset:576
	v_or_b32_e32 v146, 16, v190
	v_mov_b32_e32 v147, v191
	v_lshlrev_b64 v[218:219], 12, v[146:147]
	v_lshl_add_u64 v[158:159], v[178:179], 0, v[218:219]
	global_load_dwordx4 v[146:149], v[158:159], off
	global_load_dwordx4 v[150:153], v[158:159], off offset:64
	global_load_dwordx4 v[154:157], v[158:159], off offset:512
	s_nop 0
	global_load_dwordx4 v[158:161], v[158:159], off offset:576
	v_or_b32_e32 v162, 32, v190
	v_mov_b32_e32 v163, v191
	v_lshlrev_b64 v[220:221], 12, v[162:163]
	v_lshl_add_u64 v[174:175], v[178:179], 0, v[220:221]
	global_load_dwordx4 v[162:165], v[174:175], off
	global_load_dwordx4 v[166:169], v[174:175], off offset:64
	global_load_dwordx4 v[170:173], v[174:175], off offset:512
	s_nop 0
	global_load_dwordx4 v[174:177], v[174:175], off offset:576
	v_or_b32_e32 v180, 48, v190
	v_mov_b32_e32 v181, v191
	v_lshlrev_b64 v[222:223], 12, v[180:181]
	v_lshl_add_u64 v[214:215], v[178:179], 0, v[222:223]
	global_load_dwordx4 v[180:183], v[214:215], off
	global_load_dwordx4 v[200:203], v[214:215], off offset:64
	global_load_dwordx4 v[204:207], v[214:215], off offset:512
	s_nop 0
	global_load_dwordx4 v[214:217], v[214:215], off offset:576
	v_lshl_add_u64 v[184:185], s[16:17], 0, v[184:185]
	v_lshl_add_u64 v[184:185], v[184:185], 0, v[198:199]
	s_waitcnt vmcnt(15)
	v_pk_add_f32 v[132:133], v[128:129], v[132:133]
	v_pk_add_f32 v[130:131], v[126:127], v[130:131]
	global_store_dwordx4 v[184:185], v[130:133], off
	s_nop 1
	s_waitcnt vmcnt(15)
	v_pk_add_f32 v[132:133], v[124:125], v[136:137]
	v_pk_add_f32 v[130:131], v[122:123], v[134:135]
	global_store_dwordx4 v[184:185], v[130:133], off offset:64
	s_nop 1
	s_waitcnt vmcnt(15)
	v_pk_add_f32 v[132:133], v[120:121], v[140:141]
	v_pk_add_f32 v[130:131], v[118:119], v[138:139]
	global_store_dwordx4 v[184:185], v[130:133], off offset:512
	s_nop 1
	s_waitcnt vmcnt(15)
	v_pk_add_f32 v[132:133], v[116:117], v[144:145]
	v_pk_add_f32 v[130:131], v[114:115], v[142:143]
	global_store_dwordx4 v[184:185], v[130:133], off offset:576
	s_nop 1
	v_lshl_add_u64 v[130:131], s[16:17], 0, v[218:219]
	v_lshl_add_u64 v[134:135], v[130:131], 0, v[198:199]
	s_waitcnt vmcnt(15)
	v_pk_add_f32 v[132:133], v[112:113], v[148:149]
	v_pk_add_f32 v[130:131], v[110:111], v[146:147]
	global_store_dwordx4 v[134:135], v[130:133], off
	s_nop 1
	s_waitcnt vmcnt(15)
	v_pk_add_f32 v[132:133], v[108:109], v[152:153]
	v_pk_add_f32 v[130:131], v[106:107], v[150:151]
	global_store_dwordx4 v[134:135], v[130:133], off offset:64
	s_nop 1
	s_waitcnt vmcnt(15)
	v_pk_add_f32 v[132:133], v[104:105], v[156:157]
	v_pk_add_f32 v[130:131], v[102:103], v[154:155]
	global_store_dwordx4 v[134:135], v[130:133], off offset:512
	s_nop 1
	s_waitcnt vmcnt(15)
	v_pk_add_f32 v[132:133], v[100:101], v[160:161]
	v_pk_add_f32 v[130:131], v[98:99], v[158:159]
	global_store_dwordx4 v[134:135], v[130:133], off offset:576
	s_nop 1
	v_lshl_add_u64 v[130:131], s[16:17], 0, v[220:221]
	v_lshl_add_u64 v[134:135], v[130:131], 0, v[198:199]
	s_waitcnt vmcnt(15)
	v_pk_add_f32 v[132:133], v[96:97], v[164:165]
	v_pk_add_f32 v[130:131], v[94:95], v[162:163]
	global_store_dwordx4 v[134:135], v[130:133], off
	s_nop 1
	s_waitcnt vmcnt(15)
	v_pk_add_f32 v[132:133], v[92:93], v[168:169]
	v_pk_add_f32 v[130:131], v[90:91], v[166:167]
	global_store_dwordx4 v[134:135], v[130:133], off offset:64
	s_nop 1
	s_waitcnt vmcnt(15)
	v_pk_add_f32 v[132:133], v[88:89], v[172:173]
	v_pk_add_f32 v[130:131], v[86:87], v[170:171]
	global_store_dwordx4 v[134:135], v[130:133], off offset:512
	s_nop 1
	s_waitcnt vmcnt(15)
	v_pk_add_f32 v[132:133], v[84:85], v[176:177]
	v_pk_add_f32 v[130:131], v[82:83], v[174:175]
	global_store_dwordx4 v[134:135], v[130:133], off offset:576
	s_nop 1
	v_lshl_add_u64 v[130:131], s[16:17], 0, v[222:223]
	v_lshl_add_u64 v[134:135], v[130:131], 0, v[198:199]
	s_waitcnt vmcnt(15)
	v_pk_add_f32 v[132:133], v[80:81], v[182:183]
	v_pk_add_f32 v[130:131], v[78:79], v[180:181]
	global_store_dwordx4 v[134:135], v[130:133], off
	v_add_u32_e32 v180, 0xb0, v190
	v_mov_b32_e32 v181, v191
	s_waitcnt vmcnt(15)
	v_pk_add_f32 v[132:133], v[76:77], v[202:203]
	v_pk_add_f32 v[130:131], v[74:75], v[200:201]
	global_store_dwordx4 v[134:135], v[130:133], off offset:64
	s_nop 1
	s_waitcnt vmcnt(15)
	v_pk_add_f32 v[132:133], v[72:73], v[206:207]
	v_pk_add_f32 v[130:131], v[70:71], v[204:205]
	global_store_dwordx4 v[134:135], v[130:133], off offset:512
	v_lshlrev_b64 v[206:207], 12, v[180:181]
	s_nop 0
	s_waitcnt vmcnt(15)
	v_pk_add_f32 v[132:133], v[68:69], v[216:217]
	v_pk_add_f32 v[130:131], v[66:67], v[214:215]
	global_store_dwordx4 v[134:135], v[130:133], off offset:576
	s_nop 1
	v_add_u32_e32 v130, 0x80, v190
	v_mov_b32_e32 v131, v191
	v_lshlrev_b64 v[204:205], 12, v[130:131]
	v_lshl_add_u64 v[130:131], v[178:179], 0, v[204:205]
	global_load_dwordx4 v[174:177], v[130:131], off
	global_load_dwordx4 v[170:173], v[130:131], off offset:64
	global_load_dwordx4 v[162:165], v[130:131], off offset:512
	global_load_dwordx4 v[154:157], v[130:131], off offset:576
	v_add_u32_e32 v130, 0x90, v190
	v_mov_b32_e32 v131, v191
	v_lshlrev_b64 v[202:203], 12, v[130:131]
	v_lshl_add_u64 v[130:131], v[178:179], 0, v[202:203]
	global_load_dwordx4 v[166:169], v[130:131], off
	global_load_dwordx4 v[158:161], v[130:131], off offset:64
	global_load_dwordx4 v[146:149], v[130:131], off offset:512
	global_load_dwordx4 v[138:141], v[130:131], off offset:576
	v_add_u32_e32 v130, 0xa0, v190
	v_mov_b32_e32 v131, v191
	v_lshlrev_b64 v[200:201], 12, v[130:131]
	v_lshl_add_u64 v[130:131], v[178:179], 0, v[200:201]
	global_load_dwordx4 v[150:153], v[130:131], off
	global_load_dwordx4 v[142:145], v[130:131], off offset:64
	global_load_dwordx4 v[134:137], v[130:131], off offset:512
	s_nop 0
	global_load_dwordx4 v[130:133], v[130:131], off offset:576
	v_lshl_add_u64 v[178:179], v[178:179], 0, v[206:207]
	global_load_dwordx4 v[214:217], v[178:179], off
	global_load_dwordx4 v[218:221], v[178:179], off offset:64
	global_load_dwordx4 v[182:185], v[178:179], off offset:512
	s_nop 0
	global_load_dwordx4 v[178:181], v[178:179], off offset:576
	v_lshl_add_u64 v[204:205], s[16:17], 0, v[204:205]
	v_lshl_add_u64 v[204:205], v[204:205], 0, v[198:199]
	s_waitcnt vmcnt(15)
	v_pk_add_f32 v[176:177], v[64:65], v[176:177]
	v_pk_add_f32 v[174:175], v[62:63], v[174:175]
	s_waitcnt vmcnt(13)
	v_pk_add_f32 v[164:165], v[56:57], v[164:165]
	s_waitcnt vmcnt(12)
	v_pk_add_f32 v[156:157], v[52:53], v[156:157]
	v_pk_add_f32 v[154:155], v[50:51], v[154:155]
	v_pk_add_f32 v[162:163], v[54:55], v[162:163]
	global_store_dwordx4 v[204:205], v[154:157], off offset:576
	global_store_dwordx4 v[204:205], v[162:165], off offset:512
	s_waitcnt vmcnt(10)
	v_pk_add_f32 v[140:141], v[36:37], v[140:141]
	v_lshl_add_u64 v[154:155], s[16:17], 0, v[202:203]
	v_lshl_add_u64 v[162:163], v[154:155], 0, v[198:199]
	v_pk_add_f32 v[138:139], v[34:35], v[138:139]
	v_pk_add_f32 v[148:149], v[40:41], v[148:149]
	v_pk_add_f32 v[146:147], v[38:39], v[146:147]
	global_store_dwordx4 v[162:163], v[138:141], off offset:576
	global_store_dwordx4 v[162:163], v[146:149], off offset:512
	s_waitcnt vmcnt(8)
	v_pk_add_f32 v[132:133], v[20:21], v[132:133]
	v_lshl_add_u64 v[138:139], s[16:17], 0, v[200:201]
	v_lshl_add_u64 v[146:147], v[138:139], 0, v[198:199]
	v_pk_add_f32 v[130:131], v[18:19], v[130:131]
	v_pk_add_f32 v[136:137], v[24:25], v[136:137]
	v_pk_add_f32 v[134:135], v[22:23], v[134:135]
	global_store_dwordx4 v[146:147], v[130:133], off offset:576
	global_store_dwordx4 v[146:147], v[134:137], off offset:512
	v_pk_add_f32 v[156:157], v[48:49], v[168:169]
	v_lshl_add_u64 v[130:131], s[16:17], 0, v[206:207]
	v_lshl_add_u64 v[134:135], v[130:131], 0, v[198:199]
	s_waitcnt vmcnt(9)
	v_pk_add_f32 v[132:133], v[16:17], v[216:217]
	v_pk_add_f32 v[130:131], v[14:15], v[214:215]
	global_store_dwordx4 v[134:135], v[130:133], off
	v_pk_add_f32 v[154:155], v[46:47], v[166:167]
	v_pk_add_f32 v[140:141], v[32:33], v[152:153]
	s_waitcnt vmcnt(9)
	v_pk_add_f32 v[132:133], v[12:13], v[220:221]
	v_pk_add_f32 v[130:131], v[10:11], v[218:219]
	v_pk_add_f32 v[138:139], v[30:31], v[150:151]
	global_store_dwordx4 v[134:135], v[130:133], off offset:64
	v_pk_add_f32 v[172:173], v[60:61], v[172:173]
	v_pk_add_f32 v[170:171], v[58:59], v[170:171]
	s_waitcnt vmcnt(9)
	v_pk_add_f32 v[132:133], v[8:9], v[184:185]
	v_pk_add_f32 v[130:131], v[6:7], v[182:183]
	global_store_dwordx4 v[162:163], v[154:157], off
	global_store_dwordx4 v[146:147], v[138:141], off
	global_store_dwordx4 v[134:135], v[130:133], off offset:512
	v_pk_add_f32 v[156:157], v[44:45], v[160:161]
	v_pk_add_f32 v[154:155], v[42:43], v[158:159]
	v_pk_add_f32 v[140:141], v[28:29], v[144:145]
	v_pk_add_f32 v[138:139], v[26:27], v[142:143]
	s_waitcnt vmcnt(11)
	v_pk_add_f32 v[132:133], v[4:5], v[180:181]
	v_pk_add_f32 v[130:131], v[2:3], v[178:179]
	global_store_dwordx4 v[204:205], v[174:177], off
	global_store_dwordx4 v[204:205], v[170:173], off offset:64
	global_store_dwordx4 v[162:163], v[154:157], off offset:64
	global_store_dwordx4 v[146:147], v[138:141], off offset:64
	s_cbranch_execnz .LBB0_1611
